# speedup vs baseline: 1.0092x; 1.0092x over previous
.LBB0_471:
	s_and_b32 s0, s13, 0x2000
	s_add_i32 s16, s0, 16
	s_add_i32 s16, s16, 0x20000
	v_add_u32_e32 v20, s16, v170
	v_add_u32_e32 v0, v20, v193
	v_add_u32_e32 v1, v20, v194
	ds_read_b128 v[16:19], v0
	ds_read_b128 v[206:209], v1
	v_add_u32_e32 v0, v20, v195
	v_add_u32_e32 v21, v20, v197
	v_add_u32_e32 v1, v20, v196
	ds_read_b128 v[210:213], v0
	ds_read_b128 v[214:217], v1
	v_add_u32_e32 v22, v20, v198
	ds_read_b128 v[218:221], v21
	ds_read_b128 v[222:225], v22
	v_add_u32_e32 v21, v20, v199
	v_add_u32_e32 v20, v20, v200
	ds_read_b128 v[226:229], v21
	ds_read_b128 v[230:233], v20
	v_max_f32_e32 v20, v32, v32
	s_waitcnt lgkmcnt(7)
	v_mfma_f32_32x32x16_bf16 v[0:15], v[96:99], v[16:19], 0
	v_max_f32_e32 v183, 0, v20
	v_fma_f32 v183, v92, v183, 0
	v_max_f32_e32 v236, 0, v34
	v_max_f32_e32 v205, 0, v48
	v_fmac_f32_e32 v183, v94, v236
	v_mfma_f32_32x32x16_bf16 v[16:31], v[128:131], v[16:19], 0
	v_max_f32_e32 v236, v50, v50
	v_fma_f32 v205, v88, v205, 0
	v_max_f32_e32 v234, 0, v33
	v_fma_f32 v234, v93, v234, 0
	v_max_f32_e32 v235, 0, v49
	s_waitcnt lgkmcnt(6)
	v_mfma_f32_32x32x16_bf16 v[0:15], v[100:103], v[206:209], v[0:15]
	v_fma_f32 v235, v89, v235, 0
	v_mfma_f32_32x32x16_bf16 v[16:31], v[132:135], v[206:209], v[16:31]
	v_max_f32_e32 v206, 0, v236
	v_fmac_f32_e32 v205, v90, v206
	v_max_f32_e32 v206, 0, v35
	v_fmac_f32_e32 v234, v95, v206
	v_max_f32_e32 v206, 0, v51
	v_fmac_f32_e32 v235, v91, v206
	v_max_f32_e32 v206, 0, v36
	v_fmac_f32_e32 v183, v84, v206
	v_max_f32_e32 v206, 0, v52
	v_fmac_f32_e32 v205, v80, v206
	v_max_f32_e32 v206, 0, v37
	v_fmac_f32_e32 v234, v85, v206
	v_max_f32_e32 v206, 0, v53
	s_waitcnt lgkmcnt(5)
	v_mfma_f32_32x32x16_bf16 v[0:15], v[104:107], v[210:213], v[0:15]
	v_fmac_f32_e32 v235, v81, v206
	v_max_f32_e32 v206, 0, v38
	v_fmac_f32_e32 v183, v86, v206
	v_max_f32_e32 v206, 0, v54
	v_fmac_f32_e32 v205, v82, v206
	v_mfma_f32_32x32x16_bf16 v[16:31], v[136:139], v[210:213], v[16:31]
	v_max_f32_e32 v206, 0, v39
	v_fmac_f32_e32 v234, v87, v206
	v_max_f32_e32 v206, 0, v55
	v_fmac_f32_e32 v235, v83, v206
	s_waitcnt lgkmcnt(4)
	v_mfma_f32_32x32x16_bf16 v[0:15], v[108:111], v[214:217], v[0:15]
	v_max_f32_e32 v206, 0, v40
	v_fmac_f32_e32 v183, v72, v206
	v_max_f32_e32 v206, 0, v56
	s_waitcnt vmcnt(1)
	v_fmac_f32_e32 v205, v76, v206
	v_max_f32_e32 v206, 0, v41
	v_mfma_f32_32x32x16_bf16 v[16:31], v[140:143], v[214:217], v[16:31]
	v_fmac_f32_e32 v234, v73, v206
	v_max_f32_e32 v206, 0, v57
	v_fmac_f32_e32 v235, v77, v206
	v_max_f32_e32 v206, 0, v42
	v_fmac_f32_e32 v183, v74, v206
	s_waitcnt lgkmcnt(3)
	v_mfma_f32_32x32x16_bf16 v[0:15], v[112:115], v[218:221], v[0:15]
	v_max_f32_e32 v206, 0, v58
	v_fmac_f32_e32 v205, v78, v206
	v_max_f32_e32 v206, 0, v43
	v_fmac_f32_e32 v234, v75, v206
	v_mfma_f32_32x32x16_bf16 v[16:31], v[144:147], v[218:221], v[16:31]
	v_max_f32_e32 v206, 0, v59
	v_fmac_f32_e32 v235, v79, v206
	v_max_f32_e32 v206, 0, v44
	v_fmac_f32_e32 v183, v64, v206
	v_max_f32_e32 v206, 0, v60
	s_waitcnt lgkmcnt(2)
	v_mfma_f32_32x32x16_bf16 v[0:15], v[116:119], v[222:225], v[0:15]
	s_waitcnt vmcnt(0)
	v_fmac_f32_e32 v205, v68, v206
	v_max_f32_e32 v206, 0, v45
	v_fmac_f32_e32 v234, v65, v206
	v_max_f32_e32 v206, 0, v61
	v_fmac_f32_e32 v235, v69, v206
	v_mfma_f32_32x32x16_bf16 v[16:31], v[148:151], v[222:225], v[16:31]
	v_max_f32_e32 v206, 0, v46
	v_fmac_f32_e32 v183, v66, v206
	v_max_f32_e32 v206, 0, v62
	v_fmac_f32_e32 v205, v70, v206
	s_waitcnt lgkmcnt(1)
	v_mfma_f32_32x32x16_bf16 v[0:15], v[120:123], v[226:229], v[0:15]
	v_max_f32_e32 v206, 0, v47
	v_fmac_f32_e32 v234, v67, v206
	v_max_f32_e32 v206, 0, v63
	v_fmac_f32_e32 v235, v71, v206
	v_add_f32_e32 v183, v183, v205
	v_add_f32_e32 v205, v234, v235
	v_mfma_f32_32x32x16_bf16 v[16:31], v[152:155], v[226:229], v[16:31]
	v_add_f32_e32 v183, v183, v205
	ds_bpermute_b32 v205, v203, v183
	s_waitcnt lgkmcnt(1)
	v_mfma_f32_32x32x16_bf16 v[0:15], v[124:127], v[230:233], v[0:15]
	v_mfma_f32_32x32x16_bf16 v[16:31], v[156:159], v[230:233], v[16:31]
	s_and_saveexec_b64 s[0:1], s[4:5]
	s_cbranch_execz .LBB0_473
	s_waitcnt lgkmcnt(0)
	v_add_f32_e32 v183, v183, v205
	ds_write_b32 v204, v183

.LBB0_477:
	s_add_i32 s0, s13, 0x2000
	s_and_b32 s0, s0, 0x2000
	v_add_u32_e32 v52, s0, v188
	v_add_u32_e32 v32, v52, v193
	v_add_u32_e32 v33, v52, v194
	ds_read_b128 v[48:51], v32
	ds_read_b128 v[206:209], v33
	v_add_u32_e32 v32, v52, v195
	v_add_u32_e32 v53, v52, v197
	v_add_u32_e32 v33, v52, v196
	ds_read_b128 v[210:213], v32
	ds_read_b128 v[214:217], v33
	v_add_u32_e32 v54, v52, v198
	ds_read_b128 v[218:221], v53
	ds_read_b128 v[222:225], v54
	v_add_u32_e32 v53, v52, v199
	v_add_u32_e32 v52, v52, v200
	ds_read_b128 v[226:229], v53
	ds_read_b128 v[230:233], v52
	v_max_f32_e32 v52, v0, v0
	s_waitcnt lgkmcnt(7)
	v_mfma_f32_32x32x16_bf16 v[32:47], v[96:99], v[48:51], 0
	v_max_f32_e32 v183, 0, v52
	v_fma_f32 v183, v92, v183, 0
	v_max_f32_e32 v236, 0, v2
	v_max_f32_e32 v205, 0, v16
	v_fmac_f32_e32 v183, v94, v236
	v_mfma_f32_32x32x16_bf16 v[48:63], v[128:131], v[48:51], 0
	v_max_f32_e32 v236, v18, v18
	v_fma_f32 v205, v88, v205, 0
	v_max_f32_e32 v234, 0, v1
	v_fma_f32 v234, v93, v234, 0
	v_max_f32_e32 v235, 0, v17
	s_waitcnt lgkmcnt(6)
	v_mfma_f32_32x32x16_bf16 v[32:47], v[100:103], v[206:209], v[32:47]
	v_fma_f32 v235, v89, v235, 0
	v_mfma_f32_32x32x16_bf16 v[48:63], v[132:135], v[206:209], v[48:63]
	v_max_f32_e32 v206, 0, v236
	v_fmac_f32_e32 v205, v90, v206
	v_max_f32_e32 v206, 0, v3
	v_fmac_f32_e32 v234, v95, v206
	v_max_f32_e32 v206, 0, v19
	v_fmac_f32_e32 v235, v91, v206
	v_max_f32_e32 v206, 0, v4
	v_fmac_f32_e32 v183, v84, v206
	v_max_f32_e32 v206, 0, v20
	v_fmac_f32_e32 v205, v80, v206
	v_max_f32_e32 v206, 0, v5
	v_fmac_f32_e32 v234, v85, v206
	v_max_f32_e32 v206, 0, v21
	s_waitcnt lgkmcnt(5)
	v_mfma_f32_32x32x16_bf16 v[32:47], v[104:107], v[210:213], v[32:47]
	v_fmac_f32_e32 v235, v81, v206
	v_max_f32_e32 v206, 0, v6
	v_fmac_f32_e32 v183, v86, v206
	v_max_f32_e32 v206, 0, v22
	v_fmac_f32_e32 v205, v82, v206
	v_mfma_f32_32x32x16_bf16 v[48:63], v[136:139], v[210:213], v[48:63]
	v_max_f32_e32 v206, 0, v7
	v_fmac_f32_e32 v234, v87, v206
	v_max_f32_e32 v206, 0, v23
	v_fmac_f32_e32 v235, v83, v206
	s_waitcnt lgkmcnt(4)
	v_mfma_f32_32x32x16_bf16 v[32:47], v[108:111], v[214:217], v[32:47]
	v_max_f32_e32 v206, 0, v8
	v_fmac_f32_e32 v183, v72, v206
	v_max_f32_e32 v206, 0, v24
	v_fmac_f32_e32 v205, v76, v206
	v_max_f32_e32 v206, 0, v9
	v_mfma_f32_32x32x16_bf16 v[48:63], v[140:143], v[214:217], v[48:63]
	v_fmac_f32_e32 v234, v73, v206
	v_max_f32_e32 v206, 0, v25
	v_fmac_f32_e32 v235, v77, v206
	v_max_f32_e32 v206, 0, v10
	v_fmac_f32_e32 v183, v74, v206
	s_waitcnt lgkmcnt(3)
	v_mfma_f32_32x32x16_bf16 v[32:47], v[112:115], v[218:221], v[32:47]
	v_max_f32_e32 v206, 0, v26
	v_fmac_f32_e32 v205, v78, v206
	v_max_f32_e32 v206, 0, v11
	v_fmac_f32_e32 v234, v75, v206
	v_mfma_f32_32x32x16_bf16 v[48:63], v[144:147], v[218:221], v[48:63]
	v_max_f32_e32 v206, 0, v27
	v_fmac_f32_e32 v235, v79, v206
	v_max_f32_e32 v206, 0, v12
	v_fmac_f32_e32 v183, v64, v206
	v_max_f32_e32 v206, 0, v28
	s_waitcnt lgkmcnt(2)
	v_mfma_f32_32x32x16_bf16 v[32:47], v[116:119], v[222:225], v[32:47]
	v_fmac_f32_e32 v205, v68, v206
	v_max_f32_e32 v206, 0, v13
	v_fmac_f32_e32 v234, v65, v206
	v_max_f32_e32 v206, 0, v29
	v_fmac_f32_e32 v235, v69, v206
	v_mfma_f32_32x32x16_bf16 v[48:63], v[148:151], v[222:225], v[48:63]
	v_max_f32_e32 v206, 0, v14
	v_fmac_f32_e32 v183, v66, v206
	v_max_f32_e32 v206, 0, v30
	v_fmac_f32_e32 v205, v70, v206
	s_waitcnt lgkmcnt(1)
	v_mfma_f32_32x32x16_bf16 v[32:47], v[120:123], v[226:229], v[32:47]
	v_max_f32_e32 v206, 0, v15
	v_fmac_f32_e32 v234, v67, v206
	v_max_f32_e32 v206, 0, v31
	v_fmac_f32_e32 v235, v71, v206
	v_add_f32_e32 v183, v183, v205
	v_add_f32_e32 v205, v234, v235
	v_mfma_f32_32x32x16_bf16 v[48:63], v[152:155], v[226:229], v[48:63]
	v_add_f32_e32 v183, v183, v205
	ds_bpermute_b32 v205, v203, v183
	s_waitcnt lgkmcnt(1)
	v_mfma_f32_32x32x16_bf16 v[32:47], v[124:127], v[230:233], v[32:47]
	v_mfma_f32_32x32x16_bf16 v[48:63], v[156:159], v[230:233], v[48:63]
	s_and_saveexec_b64 s[0:1], s[4:5]
	s_cbranch_execz .LBB0_479
	s_waitcnt lgkmcnt(0)
	v_add_f32_e32 v183, v183, v205
	ds_write_b32 v204, v183 offset:128

; __device__ __forceinline__ void indexer_phase(const Params& P, char* lds) {
;     ...
;       if (nch & 1) IDX_RED(xa0, xa1, nch - 1); else IDX_RED(ya0, ya1, nch - 1);
.LBB0_482:
	s_lshl_b64 s[8:9], s[10:11], 6
	s_bitcmp0_b32 s3, 5
	s_cbranch_scc1 .LBB0_484
	s_nop 6
	v_max_f32_e32 v32, 0, v32
	v_max_f32_e32 v48, 0, v48
	v_max_f32_e32 v33, 0, v33
	v_max_f32_e32 v49, 0, v49
	v_max_f32_e32 v34, 0, v34
	v_max_f32_e32 v50, 0, v50
	v_max_f32_e32 v35, 0, v35
	v_max_f32_e32 v51, 0, v51
	v_pk_fma_f32 v[32:33], v[92:93], v[32:33], 0 op_sel_hi:[1,1,0]
	v_pk_fma_f32 v[48:49], v[88:89], v[48:49], 0 op_sel_hi:[1,1,0]
	v_max_f32_e32 v36, 0, v36
	v_max_f32_e32 v52, 0, v52
	v_max_f32_e32 v37, 0, v37
	v_max_f32_e32 v53, 0, v53
	v_pk_fma_f32 v[32:33], v[94:95], v[34:35], v[32:33]
	v_pk_fma_f32 v[34:35], v[90:91], v[50:51], v[48:49]
	v_max_f32_e32 v38, 0, v38
	v_max_f32_e32 v54, 0, v54
	v_max_f32_e32 v39, 0, v39
	v_max_f32_e32 v55, 0, v55
	v_pk_fma_f32 v[32:33], v[84:85], v[36:37], v[32:33]
	v_pk_fma_f32 v[34:35], v[80:81], v[52:53], v[34:35]
	v_max_f32_e32 v40, 0, v40
	v_max_f32_e32 v56, 0, v56
	v_max_f32_e32 v41, 0, v41
	v_max_f32_e32 v57, 0, v57
	v_pk_fma_f32 v[32:33], v[86:87], v[38:39], v[32:33]
	v_pk_fma_f32 v[34:35], v[82:83], v[54:55], v[34:35]
	v_max_f32_e32 v42, 0, v42
	v_max_f32_e32 v58, 0, v58
	v_max_f32_e32 v43, 0, v43
	v_max_f32_e32 v59, 0, v59
	v_pk_fma_f32 v[32:33], v[72:73], v[40:41], v[32:33]
	s_waitcnt vmcnt(1)
	v_pk_fma_f32 v[34:35], v[76:77], v[56:57], v[34:35]
	v_max_f32_e32 v44, 0, v44
	v_max_f32_e32 v60, 0, v60
	v_max_f32_e32 v45, 0, v45
	v_max_f32_e32 v61, 0, v61
	v_pk_fma_f32 v[32:33], v[74:75], v[42:43], v[32:33]
	v_pk_fma_f32 v[34:35], v[78:79], v[58:59], v[34:35]
	v_max_f32_e32 v46, 0, v46
	v_max_f32_e32 v62, 0, v62
	v_max_f32_e32 v47, 0, v47
	v_max_f32_e32 v63, 0, v63
	v_pk_fma_f32 v[32:33], v[64:65], v[44:45], v[32:33]
	s_waitcnt vmcnt(0)
	v_pk_fma_f32 v[34:35], v[68:69], v[60:61], v[34:35]
	v_pk_fma_f32 v[32:33], v[66:67], v[46:47], v[32:33]
	v_pk_fma_f32 v[34:35], v[70:71], v[62:63], v[34:35]
	s_nop 0
	v_pk_add_f32 v[32:33], v[34:35], v[32:33]
	v_and_b32_e32 v34, 64, v202
	v_add_f32_e32 v32, v32, v33
	v_xor_b32_e32 v33, 32, v202
	v_add_u32_e32 v34, 64, v34
	v_cmp_lt_i32_e32 vcc, v33, v34
	s_and_b64 s[10:11], s[4:5], exec
	s_nop 0
	v_cndmask_b32_e32 v33, v202, v33, vcc
	v_lshlrev_b32_e32 v33, 2, v33
	ds_bpermute_b32 v33, v33, v32
	s_movk_i32 s12, 0xffe0
	s_cbranch_execz .LBB0_485
	s_branch .LBB0_486

; __device__ __forceinline__ void indexer_phase(const Params& P, char* lds) {
;     ...
;       if (nch & 1) IDX_RED(xa0, xa1, nch - 1); else IDX_RED(ya0, ya1, nch - 1);
.LBB0_485:
	s_waitcnt lgkmcnt(0)
	s_nop 3
	v_max_f32_e32 v33, v16, v16
	v_max_f32_e32 v34, 0, v33
	v_max_f32_e32 v37, v18, v18
	v_max_f32_e32 v32, 0, v0
	v_max_f32_e32 v33, 0, v1
	v_max_f32_e32 v35, 0, v17
	v_max_f32_e32 v38, 0, v37
	v_max_f32_e32 v41, v20, v20
	v_max_f32_e32 v36, 0, v2
	v_max_f32_e32 v37, 0, v3
	v_max_f32_e32 v39, 0, v19
	v_max_f32_e32 v42, 0, v41
	v_max_f32_e32 v45, v22, v22
	v_pk_fma_f32 v[32:33], v[92:93], v[32:33], 0 op_sel_hi:[1,1,0]
	v_pk_fma_f32 v[34:35], v[88:89], v[34:35], 0 op_sel_hi:[1,1,0]
	v_max_f32_e32 v40, 0, v4
	v_max_f32_e32 v41, 0, v5
	v_max_f32_e32 v43, 0, v21
	v_max_f32_e32 v46, 0, v45
	v_max_f32_e32 v49, v24, v24
	v_pk_fma_f32 v[32:33], v[94:95], v[36:37], v[32:33]
	v_pk_fma_f32 v[34:35], v[90:91], v[38:39], v[34:35]
	v_max_f32_e32 v44, 0, v6
	v_max_f32_e32 v45, 0, v7
	v_max_f32_e32 v47, 0, v23
	v_max_f32_e32 v50, 0, v49
	v_max_f32_e32 v53, v26, v26
	v_pk_fma_f32 v[32:33], v[84:85], v[40:41], v[32:33]
	v_pk_fma_f32 v[34:35], v[80:81], v[42:43], v[34:35]
	v_max_f32_e32 v48, 0, v8
	v_max_f32_e32 v49, 0, v9
	v_max_f32_e32 v51, 0, v25
	v_max_f32_e32 v54, 0, v53
	v_max_f32_e32 v57, v28, v28
	v_pk_fma_f32 v[32:33], v[86:87], v[44:45], v[32:33]
	v_pk_fma_f32 v[34:35], v[82:83], v[46:47], v[34:35]
	v_max_f32_e32 v52, 0, v10
	v_max_f32_e32 v53, 0, v11
	v_max_f32_e32 v55, 0, v27
	v_max_f32_e32 v58, 0, v57
	v_max_f32_e32 v61, v30, v30
	v_pk_fma_f32 v[32:33], v[72:73], v[48:49], v[32:33]
	s_waitcnt vmcnt(1)
	v_pk_fma_f32 v[34:35], v[76:77], v[50:51], v[34:35]
	v_max_f32_e32 v56, 0, v12
	v_max_f32_e32 v57, 0, v13
	v_max_f32_e32 v59, 0, v29
	v_max_f32_e32 v62, 0, v61
	v_pk_fma_f32 v[32:33], v[74:75], v[52:53], v[32:33]
	v_pk_fma_f32 v[34:35], v[78:79], v[54:55], v[34:35]
	v_max_f32_e32 v60, 0, v14
	v_max_f32_e32 v61, 0, v15
	v_max_f32_e32 v63, 0, v31
	v_pk_fma_f32 v[32:33], v[64:65], v[56:57], v[32:33]
	s_waitcnt vmcnt(0)
	v_pk_fma_f32 v[34:35], v[68:69], v[58:59], v[34:35]
	v_pk_fma_f32 v[32:33], v[66:67], v[60:61], v[32:33]
	v_pk_fma_f32 v[34:35], v[70:71], v[62:63], v[34:35]
	s_andn2_b64 s[0:1], s[10:11], exec
	v_pk_add_f32 v[32:33], v[34:35], v[32:33]
	v_and_b32_e32 v34, 64, v202
	v_add_f32_e32 v32, v32, v33
	v_xor_b32_e32 v33, 32, v202
	v_add_u32_e32 v34, 64, v34
	v_cmp_lt_i32_e32 vcc, v33, v34
	s_and_b64 s[10:11], s[4:5], exec
	s_movk_i32 s12, 0xffc0
	v_cndmask_b32_e32 v33, v202, v33, vcc
	v_lshlrev_b32_e32 v33, 2, v33
	ds_bpermute_b32 v33, v33, v32
	s_or_b64 s[10:11], s[0:1], s[10:11]
